# v62 + diff unit prologue: tile-1 K/V loads issued with tile-0 loads (counted vmcnt 5/4), lambda load hoisted out of the epilogue
# baseline (speedup 1.0000x reference)
; #define AT_LOAD(TT) do { const u16* kn_ = Kp + (size_t)((TT) << 6) * ldk; const u16* vn_ = Vt + ((TT) << 6); \
;     _Pragma("unroll") for (int pi = 0; pi < 2; ++pi) vr[pi] = *(const u32x4*)(vn_ + (size_t)64 * pi * S + voff); \
;     _Pragma("unroll") for (int pi = 0; pi < NKC; ++pi) kr[pi] = *(const u32x4*)(kn_ + 64 * pi + koff); } while (0)
; template <int DQK, int KROW, bool BIAS, bool MAPS2>
; DI void attn_core(const int t, const u16* __restrict__ Q, int ldq, const u16* __restrict__ Kp, int ldk, const u16* __restrict__ Vt, int q0,
;                   char* lds, const float* lut, float b31, f32x16 (&o)[4], float& l_out) {
;     ...
;   bf16x8 qf[NKS];
; #pragma unroll
;   for (int ks = 0; ks < NKS; ++ks) qf[ks] = *(const bf16x8*)(Q + (size_t)qrow * ldq + map * DQK + 16 * ks + 8 * hf);
; #pragma unroll
;   for (int dt = 0; dt < 4; ++dt)
; #pragma unroll
;     for (int i = 0; i < 16; ++i) o[dt][i] = 0.f;
;   float m_run = 0.f, l_run = 0.f;
;   const int ntile = (q0 >> 6) + (MAPS2 ? 2 : 4);
;   u32x4 kr[NKC], vr[2];
;   const unsigned koff = (unsigned)(t >> 3) * (unsigned)ldk + (unsigned)(t & 7) * 8u;
;   const unsigned voff = (unsigned)(t >> 3) * (unsigned)S + (unsigned)(t & 7) * 8u;
;   char* const klds = lds + (t >> 3) * KS + (t & 7) * 16;
;   char* const vlds = lds + AT_VOFF + (t >> 3) * VS + ((t & 7) >> 1) * 32 + (t & 1) * 8;
;     ...
;   AT_LOAD(0);
;   __syncthreads();
;   AT_WRITE(0);
;   AT_LOAD(1);
;   __syncthreads();
; DI void diff_unit(const Params& p, const int t, int l, int h, int qb, char* lds) {
;   float* lut = (float*)(lds + LUT_OFF);
;   const int lane = t & 63, w = t >> 6, r = lane & 31, hf = lane >> 5, wr = w & 3, map = w >> 2;
;   __syncthreads();
;   if (t < 132) lut[t] = p.BLUT[h * 132 + (t > 128 ? 128 : t)];
;   const float b31 = p.BLUT[h * 132 + 128];
;   const int q0 = qb * 128, qrow = q0 + 32 * wr + r;
;   f32x16 o[4]; float lsum;
;   attn_core<64, 128, true, true>(t, p.QA + h * 128, 1024, p.KA + h * 128, 1024, p.VAT + (size_t)h * 128 * S, q0, lds, lut, b31, o, lsum);
.LBB0_226:
	s_or_b64 exec, exec, s[0:1]
	s_waitcnt lgkmcnt(0)
	s_barrier
	ds_read_b32 v0, v224
	s_waitcnt lgkmcnt(0)
	v_cmp_gt_i32_e32 vcc, 0, v0
	v_readfirstlane_b32 s0, v0
	s_cbranch_vccnz .LBB0_245
	s_mul_hi_u32 s1, s0, 0xaaaaaaab
	s_lshr_b32 s62, s1, 6
	s_mul_i32 s63, s62, 0xffffffa0
	s_add_i32 s63, s63, s0
	v_mov_b32_e32 v233, v222
	s_cmp_gt_i32 s63, 10
	s_mov_b64 s[0:1], -1
	s_cbranch_scc0 .LBB0_266
	s_add_i32 s0, s63, -11
	s_lshr_b32 s2, s0, 2
	s_and_b32 s90, s0, 3
	s_cmpk_gt_u32 s0, 0x53
	s_cselect_b64 s[0:1], -1, 0
	s_cmp_lg_u32 s90, 3
	s_cselect_b64 s[88:89], -1, 0
	s_or_b64 s[88:89], s[0:1], s[88:89]
	s_mov_b64 s[0:1], -1
	s_and_b64 vcc, exec, s[88:89]
	s_cbranch_vccz .LBB0_252
	global_load_dword v184, v1, s[82:83]
	s_movk_i32 s0, 0x13c
	v_cmp_gt_i32_e32 vcc, s0, v233
	s_mul_i32 s4, s62, 0x84
	s_barrier
	s_and_saveexec_b64 s[0:1], vcc
	s_cbranch_execz .LBB0_231
	v_add_u32_e32 v0, 0xffffffa2, v233
	v_med3_i32 v2, v0, 0, v229
	v_add_u32_e32 v2, s4, v2
	v_readlane_b32 s64, v241, 1
	v_ashrrev_i32_e32 v3, 31, v2
	v_readlane_b32 s68, v241, 5
	v_readlane_b32 s69, v241, 6
	v_readlane_b32 s65, v241, 2
	v_readlane_b32 s66, v241, 3
	v_lshl_add_u64 v[2:3], v[2:3], 2, s[68:69]
	global_load_dword v4, v[2:3], off
	v_lshlrev_b32_e32 v2, 2, v233
	v_add_u32_e32 v2, 0x16000, v2
	v_cmp_gt_i32_e32 vcc, 0, v0
	v_readlane_b32 s67, v241, 4
	v_readlane_b32 s70, v241, 7
	v_readlane_b32 s71, v241, 8
	s_waitcnt vmcnt(0)
	v_cndmask_b32_e32 v0, v4, v230, vcc
	ds_write_b32 v2, v0
.LBB0_231:
	s_or_b64 exec, exec, s[0:1]
	s_mul_i32 s0, s2, 3
	s_add_i32 s1, s0, s90
	v_readlane_b32 s64, v241, 1
	s_sub_i32 s0, 63, s1
	s_lshl_b64 s[88:89], s[4:5], 2
	v_readlane_b32 s68, v241, 5
	v_readlane_b32 s69, v241, 6
	s_add_u32 s88, s68, s88
	v_lshrrev_b32_e32 v0, 1, v233
	s_addc_u32 s89, s69, s89
	s_lshl_b32 s53, s0, 7
	v_and_b32_e32 v2, 0x60, v0
	s_waitcnt vmcnt(2)
	v_and_b32_e32 v150, 31, v233
	v_mov_b32_e32 v151, 0
	s_lshl_b32 s4, s62, 7
	v_or_b32_e32 v153, s53, v2
	global_load_dword v152, v151, s[88:89] offset:512
	s_lshl_b64 s[88:89], s[4:5], 1
	v_or_b32_e32 v144, v153, v150
	s_add_u32 s92, s42, s88
	v_ashrrev_i32_e32 v4, 8, v233
	v_ashrrev_i32_e32 v145, 31, v144
	s_addc_u32 s93, s43, s89
	v_lshlrev_b64 v[6:7], 11, v[144:145]
	v_lshlrev_b32_e32 v8, 6, v4
	v_bfe_u32 v3, v233, 5, 1
	v_lshl_add_u64 v[6:7], s[92:93], 0, v[6:7]
	v_ashrrev_i32_e32 v9, 31, v8
	v_lshl_add_u64 v[6:7], v[8:9], 1, v[6:7]
	v_lshlrev_b32_e32 v0, 4, v3
	s_add_u32 s94, s44, s88
	v_lshl_add_u64 v[6:7], v[6:7], 0, v[0:1]
	s_addc_u32 s95, s45, s89
	s_lshl_b64 s[96:97], s[4:5], 14
	global_load_dwordx4 v[112:115], v[6:7], off
	global_load_dwordx4 v[116:119], v[6:7], off offset:32
	global_load_dwordx4 v[120:123], v[6:7], off offset:64
	global_load_dwordx4 v[124:127], v[6:7], off offset:96
	v_and_b32_e32 v7, 7, v233
	s_add_u32 s96, s46, s96
	v_ashrrev_i32_e32 v5, 3, v233
	v_lshlrev_b32_e32 v14, 3, v7
	s_addc_u32 s97, s47, s97
	v_lshl_or_b32 v6, v5, 13, v14
	v_mul_lo_u32 v24, v5, s73
	v_lshlrev_b32_e32 v25, 4, v7
	v_mov_b32_e32 v7, v1
	v_lshl_or_b32 v14, v5, 10, v14
	v_lshlrev_b32_e32 v5, 7, v5
	v_and_b32_e32 v15, 0x60, v25
	v_lshl_add_u64 v[146:147], v[6:7], 1, s[96:97]
	v_sub_u32_e32 v5, v24, v5
	v_add_co_u32_e32 v22, vcc, s74, v146
	v_add_u32_e32 v5, v5, v15
	v_mov_b32_e32 v15, v1
	v_addc_co_u32_e32 v23, vcc, 0, v147, vcc
	v_lshl_add_u64 v[148:149], v[14:15], 1, s[94:95]
	global_load_dwordx4 v[6:9], v[146:147], off
	global_load_dwordx4 v[10:13], v[22:23], off
	global_load_dwordx4 v[14:17], v[148:149], off
	global_load_dwordx4 v[18:21], v[148:149], off offset:128
	v_add_co_u32_e32 v186, vcc, 0x20000, v148
	s_nop 1
	v_addc_co_u32_e32 v187, vcc, 0, v149, vcc
	global_load_dwordx4 v[128:131], v[146:147], off offset:128
	global_load_dwordx4 v[132:135], v[22:23], off offset:128
	global_load_dwordx4 v[136:139], v[186:187], off
	global_load_dwordx4 v[140:143], v[186:187], off offset:128
	v_lshlrev_b32_e32 v26, 3, v233
	s_waitcnt vmcnt(14)
	v_and_or_b32 v154, v26, 8, v5
	v_add_u32_e32 v145, v24, v25
	v_add_u32_e32 v5, 0xc800, v154
	s_waitcnt lgkmcnt(0)
	s_barrier
	s_mov_b64 s[92:93], 0x20000
	s_cmp_gt_u32 s1, 63
	v_readlane_b32 s65, v241, 2
	v_readlane_b32 s66, v241, 3
	v_readlane_b32 s67, v241, 4
	v_readlane_b32 s70, v241, 7
	v_readlane_b32 s71, v241, 8
	s_waitcnt vmcnt(5)
	ds_write_b128 v145, v[14:17]
	s_waitcnt vmcnt(4)
	ds_write_b128 v145, v[18:21] offset:128
	ds_write2_b64 v5, v[6:7], v[8:9] offset1:2
	v_add_u32_e32 v5, 0xe800, v154
	ds_write2_b64 v5, v[10:11], v[12:13] offset0:128 offset1:130
	s_waitcnt lgkmcnt(0)
	s_barrier
	s_cbranch_scc1 .LBB0_246
	s_lshl_b32 s4, s0, 1
	v_mad_u32_u24 v0, v150, s73, v0
	v_lshlrev_b32_e32 v157, 2, v3
	v_lshlrev_b32_e32 v3, 7, v150
	s_lshl_b32 s0, s90, 7
	v_lshl_add_u32 v156, v4, 7, v0
	v_sub_u32_e32 v158, v0, v3
	v_subrev_u32_e32 v0, s0, v2
	s_mul_i32 s0, s2, 0x180
	v_subrev_u32_e32 v0, s0, v0
	v_mov_b32_e32 v14, v1
	v_mov_b32_e32 v15, v1
	v_add_u32_e32 v159, 0x1f41, v0
	v_mov_b32_e32 v0, v1
	v_mov_b32_e32 v2, v1
	v_mov_b32_e32 v3, v1
	v_mov_b32_e32 v4, v1
	v_mov_b32_e32 v5, v1
	v_mov_b32_e32 v6, v1
	v_mov_b32_e32 v7, v1
	v_mov_b32_e32 v8, v1
	v_mov_b32_e32 v9, v1
	v_mov_b32_e32 v10, v1
	v_mov_b32_e32 v11, v1
	v_mov_b32_e32 v12, v1
	v_mov_b32_e32 v13, v1
	v_mov_b64_e32 v[78:79], v[14:15]
	v_mov_b64_e32 v[62:63], v[14:15]
	v_mov_b64_e32 v[46:47], v[14:15]
	v_mov_b64_e32 v[30:31], v[14:15]
	s_add_i32 s94, s4, 2
	v_or_b32_e32 v155, 31, v153
	v_sub_u32_e32 v160, v150, v157
	s_mov_b32 s90, 0
	v_mov_b32_e32 v161, 0
	v_mov_b64_e32 v[76:77], v[12:13]
	v_mov_b64_e32 v[74:75], v[10:11]
	v_mov_b64_e32 v[72:73], v[8:9]
	v_mov_b64_e32 v[70:71], v[6:7]
	v_mov_b64_e32 v[68:69], v[4:5]
	v_mov_b64_e32 v[66:67], v[2:3]
	v_mov_b64_e32 v[64:65], v[0:1]
	v_mov_b64_e32 v[60:61], v[12:13]
	v_mov_b64_e32 v[58:59], v[10:11]
	v_mov_b64_e32 v[56:57], v[8:9]
	v_mov_b64_e32 v[54:55], v[6:7]
	v_mov_b64_e32 v[52:53], v[4:5]
	v_mov_b64_e32 v[50:51], v[2:3]
	v_mov_b64_e32 v[48:49], v[0:1]
	v_mov_b64_e32 v[44:45], v[12:13]
	v_mov_b64_e32 v[42:43], v[10:11]
	v_mov_b64_e32 v[40:41], v[8:9]
	v_mov_b64_e32 v[38:39], v[6:7]
	v_mov_b64_e32 v[36:37], v[4:5]
	v_mov_b64_e32 v[34:35], v[2:3]
	v_mov_b64_e32 v[32:33], v[0:1]
	v_mov_b64_e32 v[28:29], v[12:13]
	v_mov_b64_e32 v[26:27], v[10:11]
	v_mov_b64_e32 v[24:25], v[8:9]
	v_mov_b64_e32 v[22:23], v[6:7]
	v_mov_b64_e32 v[20:21], v[4:5]
	v_mov_b64_e32 v[18:19], v[2:3]
	v_mov_b64_e32 v[16:17], v[0:1]
	v_mov_b32_e32 v151, 0
	s_mov_b32 s96, 0
	s_add_i32 s95, s96, 1
	s_cmp_ge_i32 s95, s94
	s_cbranch_scc1 .LBB0_235

; DI void diff_unit(const Params& p, const int t, int l, int h, int qb, char* lds) {
;     ...
;   float* ex = (float*)lds + (wr * 64) * 64 + lane;
;   if (map == 1) {
;     const float inv = p.LAM[l] / lsum;
; #pragma unroll
;     for (int dt = 0; dt < 4; ++dt)
; #pragma unroll
;       for (int i = 0; i < 16; ++i) ex[(dt * 16 + i) * 64] = o[dt][i] * inv;
;   }
.LBB0_247:
	v_mov_b32_e32 v2, v151
	v_and_b32_e32 v0, 63, v233
	s_nop 0
	v_permlane32_swap_b32_e32 v151, v2
	v_bfe_u32 v3, v233, 6, 2
	v_add_f32_e32 v158, v151, v2
	v_lshlrev_b32_e32 v2, 2, v0
	v_and_b32_e32 v4, 0xffffff00, v233
	v_lshl_or_b32 v2, v3, 14, v2
	v_cmp_eq_u32_e32 vcc, s60, v4
	s_and_saveexec_b64 s[0:1], vcc
	s_cbranch_execz .LBB0_249
	v_mov_b32_e32 v4, v184
	s_waitcnt vmcnt(0)
	v_div_scale_f32 v5, s[90:91], v158, v158, v4
	v_rcp_f32_e32 v6, v5
	s_nop 0
	v_fma_f32 v7, -v5, v6, 1.0
	v_fmac_f32_e32 v6, v7, v6
	v_div_scale_f32 v7, vcc, v4, v158, v4
	v_mul_f32_e32 v8, v7, v6
	v_fma_f32 v9, -v5, v8, v7
	v_fmac_f32_e32 v8, v9, v6
	v_fma_f32 v5, -v5, v8, v7
	v_div_fmas_f32 v5, v5, v6, v8
	v_div_fixup_f32 v4, v5, v158, v4
	v_mul_f32_e32 v5, v64, v4
	v_mul_f32_e32 v6, v65, v4
	ds_write2st64_b32 v2, v5, v6 offset1:1
	v_mul_f32_e32 v5, v66, v4
	v_mul_f32_e32 v6, v67, v4
	ds_write2st64_b32 v2, v5, v6 offset0:2 offset1:3
	v_mul_f32_e32 v5, v68, v4
	v_mul_f32_e32 v6, v69, v4
	ds_write2st64_b32 v2, v5, v6 offset0:4 offset1:5
	v_mul_f32_e32 v5, v70, v4
	v_mul_f32_e32 v6, v71, v4
	ds_write2st64_b32 v2, v5, v6 offset0:6 offset1:7
	v_mul_f32_e32 v5, v72, v4
	v_mul_f32_e32 v6, v73, v4
	ds_write2st64_b32 v2, v5, v6 offset0:8 offset1:9
	v_mul_f32_e32 v5, v74, v4
	v_mul_f32_e32 v6, v75, v4
	ds_write2st64_b32 v2, v5, v6 offset0:10 offset1:11
	v_mul_f32_e32 v5, v76, v4
	v_mul_f32_e32 v6, v77, v4
	ds_write2st64_b32 v2, v5, v6 offset0:12 offset1:13
	v_mul_f32_e32 v5, v78, v4
	v_mul_f32_e32 v6, v79, v4
	ds_write2st64_b32 v2, v5, v6 offset0:14 offset1:15
	v_mul_f32_e32 v5, v48, v4
	v_mul_f32_e32 v6, v49, v4
	ds_write2st64_b32 v2, v5, v6 offset0:16 offset1:17
	v_mul_f32_e32 v5, v50, v4
	v_mul_f32_e32 v6, v51, v4
	ds_write2st64_b32 v2, v5, v6 offset0:18 offset1:19
	v_mul_f32_e32 v5, v52, v4
	v_mul_f32_e32 v6, v53, v4
	ds_write2st64_b32 v2, v5, v6 offset0:20 offset1:21
	v_mul_f32_e32 v5, v54, v4
	v_mul_f32_e32 v6, v55, v4
	ds_write2st64_b32 v2, v5, v6 offset0:22 offset1:23
	v_mul_f32_e32 v5, v56, v4
	v_mul_f32_e32 v6, v57, v4
	ds_write2st64_b32 v2, v5, v6 offset0:24 offset1:25
	v_mul_f32_e32 v5, v58, v4
	v_mul_f32_e32 v6, v59, v4
	ds_write2st64_b32 v2, v5, v6 offset0:26 offset1:27
	v_mul_f32_e32 v5, v60, v4
	v_mul_f32_e32 v6, v61, v4
	ds_write2st64_b32 v2, v5, v6 offset0:28 offset1:29
	v_mul_f32_e32 v5, v62, v4
	v_mul_f32_e32 v6, v63, v4
	ds_write2st64_b32 v2, v5, v6 offset0:30 offset1:31
	v_mul_f32_e32 v5, v32, v4
	v_mul_f32_e32 v6, v33, v4
	ds_write2st64_b32 v2, v5, v6 offset0:32 offset1:33
	v_mul_f32_e32 v5, v34, v4
	v_mul_f32_e32 v6, v35, v4
	ds_write2st64_b32 v2, v5, v6 offset0:34 offset1:35
	v_mul_f32_e32 v5, v36, v4
	v_mul_f32_e32 v6, v37, v4
	ds_write2st64_b32 v2, v5, v6 offset0:36 offset1:37
	v_mul_f32_e32 v5, v38, v4
	v_mul_f32_e32 v6, v39, v4
	ds_write2st64_b32 v2, v5, v6 offset0:38 offset1:39
	v_mul_f32_e32 v5, v40, v4
	v_mul_f32_e32 v6, v41, v4
	ds_write2st64_b32 v2, v5, v6 offset0:40 offset1:41
	v_mul_f32_e32 v5, v42, v4
	v_mul_f32_e32 v6, v43, v4
	ds_write2st64_b32 v2, v5, v6 offset0:42 offset1:43
	v_mul_f32_e32 v5, v44, v4
	v_mul_f32_e32 v6, v45, v4
	ds_write2st64_b32 v2, v5, v6 offset0:44 offset1:45
	v_mul_f32_e32 v5, v46, v4
	v_mul_f32_e32 v6, v47, v4
	ds_write2st64_b32 v2, v5, v6 offset0:46 offset1:47
	v_mul_f32_e32 v5, v16, v4
	v_mul_f32_e32 v6, v17, v4
	ds_write2st64_b32 v2, v5, v6 offset0:48 offset1:49
	v_mul_f32_e32 v5, v18, v4
	v_mul_f32_e32 v6, v19, v4
	ds_write2st64_b32 v2, v5, v6 offset0:50 offset1:51
	v_mul_f32_e32 v5, v20, v4
	v_mul_f32_e32 v6, v21, v4
	ds_write2st64_b32 v2, v5, v6 offset0:52 offset1:53
	v_mul_f32_e32 v5, v22, v4
	v_mul_f32_e32 v6, v23, v4
	ds_write2st64_b32 v2, v5, v6 offset0:54 offset1:55
	v_mul_f32_e32 v5, v24, v4
	v_mul_f32_e32 v6, v25, v4
	ds_write2st64_b32 v2, v5, v6 offset0:56 offset1:57
	v_mul_f32_e32 v5, v26, v4
	v_mul_f32_e32 v6, v27, v4
	ds_write2st64_b32 v2, v5, v6 offset0:58 offset1:59
	v_mul_f32_e32 v5, v28, v4
	v_mul_f32_e32 v6, v29, v4
	ds_write2st64_b32 v2, v5, v6 offset0:60 offset1:61
	v_mul_f32_e32 v5, v30, v4
	v_mul_f32_e32 v4, v31, v4
	ds_write2st64_b32 v2, v5, v4 offset0:62 offset1:63
